# plus batched gate/T loads (rolling 4-group window, saddr global ops, counted vmcnt) in the att-out gate-mul epilogue P12
# speedup vs baseline: 1.0054x; 1.0016x over previous
; __device__ __forceinline__ float bf_lo(unsigned u) { return __uint_as_float(u << 16); }
; __device__ __forceinline__ float bf_hi(unsigned u) { return __uint_as_float(u & 0xffff0000u); }
; __device__ __forceinline__ u32x4 pack8(f32x4 a, f32x4 b) { u32x4 w; w.x = cvt_pk_bf16(a[0], a[1]); w.y = cvt_pk_bf16(a[2], a[3]); w.z = cvt_pk_bf16(b[0], b[1]); w.w = cvt_pk_bf16(b[2], b[3]); return w; }
;     __device__ __forceinline__ void operator()(AccRef acc, const Unit& u, int wr, int wc, int fr, int fq) const {
;         const int row0 = u.pm * BM + wr * 64 + fr, col0 = u.pn * BM + wc * 32 + 8 * fq;
; #pragma unroll
;         for (int ai = 0; ai < 2; ++ai)
; #pragma unroll
;             for (int m = 0; m < 4; ++m) {
;                 const size_t off = (size_t)(row0 + ai * HALF + m * 16) * 2048 + col0;
; #pragma unroll
;                 for (int bj = 0; bj < 2; ++bj) {
;                     const u32x4 gv = *(const u32x4*)(G + off + bj * HALF);
;                     f32x4 v0 = acc[ai][bj][m][0], v1 = acc[ai][bj][m][1];
;                     v0[0] *= bf_lo(gv.x); v0[1] *= bf_hi(gv.x); v0[2] *= bf_lo(gv.y); v0[3] *= bf_hi(gv.y);
;                     v1[0] *= bf_lo(gv.z); v1[1] *= bf_hi(gv.z); v1[2] *= bf_lo(gv.w); v1[3] *= bf_hi(gv.w);
;                     if (ADD) {
;                         const u32x4 tv = *(const u32x4*)(T + off + bj * HALF);
;                         v0[0] += bf_lo(tv.x); v0[1] += bf_hi(tv.x); v0[2] += bf_lo(tv.y); v0[3] += bf_hi(tv.y);
;                         v1[0] += bf_lo(tv.z); v1[1] += bf_hi(tv.z); v1[2] += bf_lo(tv.w); v1[3] += bf_hi(tv.w);
;                     }
;                     *(u32x4*)(T + off + bj * HALF) = pack8(v0, v1);
.LBB0_716:
	v_mov_b32_e32 v144, v146
	v_mov_b32_e32 v145, v147
	s_lshl_b32 s27, s36, 8
	s_add_i32 s27, s27, s54
	v_add_u32_e32 v144, s27, v144
	s_lshl_b32 s27, s61, 8
	s_or_b32 s27, s27, s55
	v_lshl_add_u32 v152, v145, 3, s27
	v_ashrrev_i32_e32 v145, 31, v144
	v_ashrrev_i32_e32 v153, 31, v152
	v_lshlrev_b64 v[144:145], 11, v[144:145]
	v_lshl_add_u64 v[144:145], v[144:145], 0, v[152:153]
	v_lshlrev_b64 v[144:145], 1, v[144:145]
	s_andn2_b64 vcc, exec, s[0:1]
	s_mov_b64 s[0:1], -1
	global_load_dwordx4 v[160:163], v144, s[4:5]
	global_load_dwordx4 v[164:167], v144, s[6:7]
	global_load_dwordx4 v[168:171], v144, s[4:5] offset:256
	global_load_dwordx4 v[172:175], v144, s[6:7] offset:256
	v_add_u32_e32 v224, s12, v144
	global_load_dwordx4 v[176:179], v224, s[4:5]
	global_load_dwordx4 v[180:183], v224, s[6:7]
	global_load_dwordx4 v[184:187], v224, s[4:5] offset:256
	global_load_dwordx4 v[188:191], v224, s[6:7] offset:256
	v_add_u32_e32 v225, s14, v144
	global_load_dwordx4 v[192:195], v225, s[4:5]
	global_load_dwordx4 v[196:199], v225, s[6:7]
	global_load_dwordx4 v[200:203], v225, s[4:5] offset:256
	global_load_dwordx4 v[204:207], v225, s[6:7] offset:256
	v_add_u32_e32 v226, s16, v144
	global_load_dwordx4 v[208:211], v226, s[4:5]
	global_load_dwordx4 v[212:215], v226, s[6:7]
	global_load_dwordx4 v[216:219], v226, s[4:5] offset:256
	global_load_dwordx4 v[220:223], v226, s[6:7] offset:256
	s_waitcnt vmcnt(14)
	v_lshlrev_b32_e32 v152, 16, v160
	v_and_b32_e32 v160, 0xffff0000, v160
	v_lshlrev_b32_e32 v156, 16, v164
	v_and_b32_e32 v164, 0xffff0000, v164
	v_lshlrev_b32_e32 v153, 16, v161
	v_and_b32_e32 v161, 0xffff0000, v161
	v_lshlrev_b32_e32 v157, 16, v165
	v_and_b32_e32 v165, 0xffff0000, v165
	v_lshlrev_b32_e32 v154, 16, v162
	v_and_b32_e32 v162, 0xffff0000, v162
	v_lshlrev_b32_e32 v158, 16, v166
	v_and_b32_e32 v166, 0xffff0000, v166
	v_lshlrev_b32_e32 v155, 16, v163
	v_and_b32_e32 v163, 0xffff0000, v163
	v_lshlrev_b32_e32 v159, 16, v167
	v_and_b32_e32 v167, 0xffff0000, v167
	v_fmac_f32_e32 v156, v124, v152
	v_fmac_f32_e32 v164, v125, v160
	v_fmac_f32_e32 v157, v126, v153
	v_fmac_f32_e32 v165, v127, v161
	v_fmac_f32_e32 v158, v120, v154
	v_fmac_f32_e32 v166, v121, v162
	v_fmac_f32_e32 v159, v122, v155
	v_fmac_f32_e32 v167, v123, v163
	v_cvt_pk_bf16_f32 v124, v156, v164
	v_cvt_pk_bf16_f32 v125, v157, v165
	v_cvt_pk_bf16_f32 v126, v158, v166
	v_cvt_pk_bf16_f32 v127, v159, v167
	global_store_dwordx4 v144, v[124:127], s[6:7]
	s_waitcnt vmcnt(13)
	v_lshlrev_b32_e32 v152, 16, v168
	v_and_b32_e32 v168, 0xffff0000, v168
	v_lshlrev_b32_e32 v156, 16, v172
	v_and_b32_e32 v172, 0xffff0000, v172
	v_lshlrev_b32_e32 v153, 16, v169
	v_and_b32_e32 v169, 0xffff0000, v169
	v_lshlrev_b32_e32 v157, 16, v173
	v_and_b32_e32 v173, 0xffff0000, v173
	v_lshlrev_b32_e32 v154, 16, v170
	v_and_b32_e32 v170, 0xffff0000, v170
	v_lshlrev_b32_e32 v158, 16, v174
	v_and_b32_e32 v174, 0xffff0000, v174
	v_lshlrev_b32_e32 v155, 16, v171
	v_and_b32_e32 v171, 0xffff0000, v171
	v_lshlrev_b32_e32 v159, 16, v175
	v_and_b32_e32 v175, 0xffff0000, v175
	v_fmac_f32_e32 v156, v116, v152
	v_fmac_f32_e32 v172, v117, v168
	v_fmac_f32_e32 v157, v118, v153
	v_fmac_f32_e32 v173, v119, v169
	v_fmac_f32_e32 v158, v112, v154
	v_fmac_f32_e32 v174, v113, v170
	v_fmac_f32_e32 v159, v114, v155
	v_fmac_f32_e32 v175, v115, v171
	v_cvt_pk_bf16_f32 v116, v156, v172
	v_cvt_pk_bf16_f32 v117, v157, v173
	v_cvt_pk_bf16_f32 v118, v158, v174
	v_cvt_pk_bf16_f32 v119, v159, v175
	global_store_dwordx4 v144, v[116:119], s[6:7] offset:256
	v_add_u32_e32 v227, s18, v144
	global_load_dwordx4 v[160:163], v227, s[4:5]
	global_load_dwordx4 v[164:167], v227, s[6:7]
	global_load_dwordx4 v[168:171], v227, s[4:5] offset:256
	global_load_dwordx4 v[172:175], v227, s[6:7] offset:256
	s_waitcnt vmcnt(16)
	v_lshlrev_b32_e32 v152, 16, v176
	v_and_b32_e32 v176, 0xffff0000, v176
	v_lshlrev_b32_e32 v156, 16, v180
	v_and_b32_e32 v180, 0xffff0000, v180
	v_lshlrev_b32_e32 v153, 16, v177
	v_and_b32_e32 v177, 0xffff0000, v177
	v_lshlrev_b32_e32 v157, 16, v181
	v_and_b32_e32 v181, 0xffff0000, v181
	v_lshlrev_b32_e32 v154, 16, v178
	v_and_b32_e32 v178, 0xffff0000, v178
	v_lshlrev_b32_e32 v158, 16, v182
	v_and_b32_e32 v182, 0xffff0000, v182
	v_lshlrev_b32_e32 v155, 16, v179
	v_and_b32_e32 v179, 0xffff0000, v179
	v_lshlrev_b32_e32 v159, 16, v183
	v_and_b32_e32 v183, 0xffff0000, v183
	v_fmac_f32_e32 v156, v108, v152
	v_fmac_f32_e32 v180, v109, v176
	v_fmac_f32_e32 v157, v110, v153
	v_fmac_f32_e32 v181, v111, v177
	v_fmac_f32_e32 v158, v104, v154
	v_fmac_f32_e32 v182, v105, v178
	v_fmac_f32_e32 v159, v106, v155
	v_fmac_f32_e32 v183, v107, v179
	v_cvt_pk_bf16_f32 v108, v156, v180
	v_cvt_pk_bf16_f32 v109, v157, v181
	v_cvt_pk_bf16_f32 v110, v158, v182
	v_cvt_pk_bf16_f32 v111, v159, v183
	global_store_dwordx4 v224, v[108:111], s[6:7]
	s_waitcnt vmcnt(15)
	v_lshlrev_b32_e32 v152, 16, v184
	v_and_b32_e32 v184, 0xffff0000, v184
	v_lshlrev_b32_e32 v156, 16, v188
	v_and_b32_e32 v188, 0xffff0000, v188
	v_lshlrev_b32_e32 v153, 16, v185
	v_and_b32_e32 v185, 0xffff0000, v185
	v_lshlrev_b32_e32 v157, 16, v189
	v_and_b32_e32 v189, 0xffff0000, v189
	v_lshlrev_b32_e32 v154, 16, v186
	v_and_b32_e32 v186, 0xffff0000, v186
	v_lshlrev_b32_e32 v158, 16, v190
	v_and_b32_e32 v190, 0xffff0000, v190
	v_lshlrev_b32_e32 v155, 16, v187
	v_and_b32_e32 v187, 0xffff0000, v187
	v_lshlrev_b32_e32 v159, 16, v191
	v_and_b32_e32 v191, 0xffff0000, v191
	v_fmac_f32_e32 v156, v100, v152
	v_fmac_f32_e32 v188, v101, v184
	v_fmac_f32_e32 v157, v102, v153
	v_fmac_f32_e32 v189, v103, v185
	v_fmac_f32_e32 v158, v96, v154
	v_fmac_f32_e32 v190, v97, v186
	v_fmac_f32_e32 v159, v98, v155
	v_fmac_f32_e32 v191, v99, v187
	v_cvt_pk_bf16_f32 v100, v156, v188
	v_cvt_pk_bf16_f32 v101, v157, v189
	v_cvt_pk_bf16_f32 v102, v158, v190
	v_cvt_pk_bf16_f32 v103, v159, v191
	global_store_dwordx4 v224, v[100:103], s[6:7] offset:256
	v_add_u32_e32 v228, s20, v144
	global_load_dwordx4 v[176:179], v228, s[4:5]
	global_load_dwordx4 v[180:183], v228, s[6:7]
	global_load_dwordx4 v[184:187], v228, s[4:5] offset:256
	global_load_dwordx4 v[188:191], v228, s[6:7] offset:256
	s_waitcnt vmcnt(18)
; __device__ __forceinline__ float bf_lo(unsigned u) { return __uint_as_float(u << 16); }
; __device__ __forceinline__ float bf_hi(unsigned u) { return __uint_as_float(u & 0xffff0000u); }
; __device__ __forceinline__ u32x4 pack8(f32x4 a, f32x4 b) { u32x4 w; w.x = cvt_pk_bf16(a[0], a[1]); w.y = cvt_pk_bf16(a[2], a[3]); w.z = cvt_pk_bf16(b[0], b[1]); w.w = cvt_pk_bf16(b[2], b[3]); return w; }
;     __device__ __forceinline__ void operator()(AccRef acc, const Unit& u, int wr, int wc, int fr, int fq) const {
;     ...
;             for (int m = 0; m < 4; ++m) {
;                 const size_t off = (size_t)(row0 + ai * HALF + m * 16) * 2048 + col0;
; #pragma unroll
;                 for (int bj = 0; bj < 2; ++bj) {
;                     const u32x4 gv = *(const u32x4*)(G + off + bj * HALF);
;                     f32x4 v0 = acc[ai][bj][m][0], v1 = acc[ai][bj][m][1];
;                     v0[0] *= bf_lo(gv.x); v0[1] *= bf_hi(gv.x); v0[2] *= bf_lo(gv.y); v0[3] *= bf_hi(gv.y);
;                     v1[0] *= bf_lo(gv.z); v1[1] *= bf_hi(gv.z); v1[2] *= bf_lo(gv.w); v1[3] *= bf_hi(gv.w);
;                     if (ADD) {
;                         const u32x4 tv = *(const u32x4*)(T + off + bj * HALF);
;                         v0[0] += bf_lo(tv.x); v0[1] += bf_hi(tv.x); v0[2] += bf_lo(tv.y); v0[3] += bf_hi(tv.y);
;                         v1[0] += bf_lo(tv.z); v1[1] += bf_hi(tv.z); v1[2] += bf_lo(tv.w); v1[3] += bf_hi(tv.w);
;                     }
;                     *(u32x4*)(T + off + bj * HALF) = pack8(v0, v1);
;                 }
	v_lshlrev_b32_e32 v152, 16, v192
	v_and_b32_e32 v192, 0xffff0000, v192
	v_lshlrev_b32_e32 v156, 16, v196
	v_and_b32_e32 v196, 0xffff0000, v196
	v_lshlrev_b32_e32 v153, 16, v193
	v_and_b32_e32 v193, 0xffff0000, v193
	v_lshlrev_b32_e32 v157, 16, v197
	v_and_b32_e32 v197, 0xffff0000, v197
	v_lshlrev_b32_e32 v154, 16, v194
	v_and_b32_e32 v194, 0xffff0000, v194
	v_lshlrev_b32_e32 v158, 16, v198
	v_and_b32_e32 v198, 0xffff0000, v198
	v_lshlrev_b32_e32 v155, 16, v195
	v_and_b32_e32 v195, 0xffff0000, v195
	v_lshlrev_b32_e32 v159, 16, v199
	v_and_b32_e32 v199, 0xffff0000, v199
	v_fmac_f32_e32 v156, v92, v152
	v_fmac_f32_e32 v196, v93, v192
	v_fmac_f32_e32 v157, v94, v153
	v_fmac_f32_e32 v197, v95, v193
	v_fmac_f32_e32 v158, v88, v154
	v_fmac_f32_e32 v198, v89, v194
	v_fmac_f32_e32 v159, v90, v155
	v_fmac_f32_e32 v199, v91, v195
	v_cvt_pk_bf16_f32 v92, v156, v196
	v_cvt_pk_bf16_f32 v93, v157, v197
	v_cvt_pk_bf16_f32 v94, v158, v198
	v_cvt_pk_bf16_f32 v95, v159, v199
	global_store_dwordx4 v225, v[92:95], s[6:7]
	s_waitcnt vmcnt(17)
	v_lshlrev_b32_e32 v152, 16, v200
	v_and_b32_e32 v200, 0xffff0000, v200
	v_lshlrev_b32_e32 v156, 16, v204
	v_and_b32_e32 v204, 0xffff0000, v204
	v_lshlrev_b32_e32 v153, 16, v201
	v_and_b32_e32 v201, 0xffff0000, v201
	v_lshlrev_b32_e32 v157, 16, v205
	v_and_b32_e32 v205, 0xffff0000, v205
	v_lshlrev_b32_e32 v154, 16, v202
	v_and_b32_e32 v202, 0xffff0000, v202
	v_lshlrev_b32_e32 v158, 16, v206
	v_and_b32_e32 v206, 0xffff0000, v206
	v_lshlrev_b32_e32 v155, 16, v203
	v_and_b32_e32 v203, 0xffff0000, v203
	v_lshlrev_b32_e32 v159, 16, v207
	v_and_b32_e32 v207, 0xffff0000, v207
	v_fmac_f32_e32 v156, v84, v152
	v_fmac_f32_e32 v204, v85, v200
	v_fmac_f32_e32 v157, v86, v153
	v_fmac_f32_e32 v205, v87, v201
	v_fmac_f32_e32 v158, v80, v154
	v_fmac_f32_e32 v206, v81, v202
	v_fmac_f32_e32 v159, v82, v155
	v_fmac_f32_e32 v207, v83, v203
	v_cvt_pk_bf16_f32 v84, v156, v204
	v_cvt_pk_bf16_f32 v85, v157, v205
	v_cvt_pk_bf16_f32 v86, v158, v206
	v_cvt_pk_bf16_f32 v87, v159, v207
	global_store_dwordx4 v225, v[84:87], s[6:7] offset:256
	v_add_u32_e32 v229, s22, v144
	global_load_dwordx4 v[192:195], v229, s[4:5]
	global_load_dwordx4 v[196:199], v229, s[6:7]
	global_load_dwordx4 v[200:203], v229, s[4:5] offset:256
	global_load_dwordx4 v[204:207], v229, s[6:7] offset:256
	s_waitcnt vmcnt(20)
	v_lshlrev_b32_e32 v152, 16, v208
	v_and_b32_e32 v208, 0xffff0000, v208
	v_lshlrev_b32_e32 v156, 16, v212
	v_and_b32_e32 v212, 0xffff0000, v212
	v_lshlrev_b32_e32 v153, 16, v209
	v_and_b32_e32 v209, 0xffff0000, v209
	v_lshlrev_b32_e32 v157, 16, v213
	v_and_b32_e32 v213, 0xffff0000, v213
	v_lshlrev_b32_e32 v154, 16, v210
	v_and_b32_e32 v210, 0xffff0000, v210
	v_lshlrev_b32_e32 v158, 16, v214
	v_and_b32_e32 v214, 0xffff0000, v214
	v_lshlrev_b32_e32 v155, 16, v211
	v_and_b32_e32 v211, 0xffff0000, v211
	v_lshlrev_b32_e32 v159, 16, v215
	v_and_b32_e32 v215, 0xffff0000, v215
	v_fmac_f32_e32 v156, v76, v152
	v_fmac_f32_e32 v212, v77, v208
	v_fmac_f32_e32 v157, v78, v153
	v_fmac_f32_e32 v213, v79, v209
	v_fmac_f32_e32 v158, v72, v154
	v_fmac_f32_e32 v214, v73, v210
	v_fmac_f32_e32 v159, v74, v155
	v_fmac_f32_e32 v215, v75, v211
	v_cvt_pk_bf16_f32 v76, v156, v212
	v_cvt_pk_bf16_f32 v77, v157, v213
	v_cvt_pk_bf16_f32 v78, v158, v214
	v_cvt_pk_bf16_f32 v79, v159, v215
	global_store_dwordx4 v226, v[76:79], s[6:7]
	s_waitcnt vmcnt(19)
	v_lshlrev_b32_e32 v152, 16, v216
	v_and_b32_e32 v216, 0xffff0000, v216
	v_lshlrev_b32_e32 v156, 16, v220
	v_and_b32_e32 v220, 0xffff0000, v220
	v_lshlrev_b32_e32 v153, 16, v217
	v_and_b32_e32 v217, 0xffff0000, v217
	v_lshlrev_b32_e32 v157, 16, v221
	v_and_b32_e32 v221, 0xffff0000, v221
	v_lshlrev_b32_e32 v154, 16, v218
	v_and_b32_e32 v218, 0xffff0000, v218
	v_lshlrev_b32_e32 v158, 16, v222
	v_and_b32_e32 v222, 0xffff0000, v222
	v_lshlrev_b32_e32 v155, 16, v219
	v_and_b32_e32 v219, 0xffff0000, v219
	v_lshlrev_b32_e32 v159, 16, v223
	v_and_b32_e32 v223, 0xffff0000, v223
	v_fmac_f32_e32 v156, v68, v152
	v_fmac_f32_e32 v220, v69, v216
	v_fmac_f32_e32 v157, v70, v153
	v_fmac_f32_e32 v221, v71, v217
	v_fmac_f32_e32 v158, v64, v154
	v_fmac_f32_e32 v222, v65, v218
	v_fmac_f32_e32 v159, v66, v155
	v_fmac_f32_e32 v223, v67, v219
	v_cvt_pk_bf16_f32 v68, v156, v220
	v_cvt_pk_bf16_f32 v69, v157, v221
	v_cvt_pk_bf16_f32 v70, v158, v222
	v_cvt_pk_bf16_f32 v71, v159, v223
	global_store_dwordx4 v226, v[68:71], s[6:7] offset:256
	v_add_u32_e32 v230, s24, v144
	global_load_dwordx4 v[208:211], v230, s[4:5]
	global_load_dwordx4 v[212:215], v230, s[6:7]
	global_load_dwordx4 v[216:219], v230, s[4:5] offset:256
	global_load_dwordx4 v[220:223], v230, s[6:7] offset:256
	s_waitcnt vmcnt(20)
	v_lshlrev_b32_e32 v152, 16, v160
	v_and_b32_e32 v160, 0xffff0000, v160
	v_lshlrev_b32_e32 v156, 16, v164
	v_and_b32_e32 v164, 0xffff0000, v164
	v_lshlrev_b32_e32 v153, 16, v161
	v_and_b32_e32 v161, 0xffff0000, v161
	v_lshlrev_b32_e32 v157, 16, v165
	v_and_b32_e32 v165, 0xffff0000, v165
	v_lshlrev_b32_e32 v154, 16, v162
	v_and_b32_e32 v162, 0xffff0000, v162
	v_lshlrev_b32_e32 v158, 16, v166
	v_and_b32_e32 v166, 0xffff0000, v166
	v_lshlrev_b32_e32 v155, 16, v163
	v_and_b32_e32 v163, 0xffff0000, v163
	v_lshlrev_b32_e32 v159, 16, v167
	v_and_b32_e32 v167, 0xffff0000, v167
	v_fmac_f32_e32 v156, v60, v152
	v_fmac_f32_e32 v164, v61, v160
	v_fmac_f32_e32 v157, v62, v153
	v_fmac_f32_e32 v165, v63, v161
	v_fmac_f32_e32 v158, v56, v154
	v_fmac_f32_e32 v166, v57, v162
	v_fmac_f32_e32 v159, v58, v155
	v_fmac_f32_e32 v167, v59, v163
	v_cvt_pk_bf16_f32 v60, v156, v164
	v_cvt_pk_bf16_f32 v61, v157, v165
	v_cvt_pk_bf16_f32 v62, v158, v166
	v_cvt_pk_bf16_f32 v63, v159, v167
	global_store_dwordx4 v227, v[60:63], s[6:7]
	s_waitcnt vmcnt(19)
; __device__ __forceinline__ float bf_lo(unsigned u) { return __uint_as_float(u << 16); }
; __device__ __forceinline__ float bf_hi(unsigned u) { return __uint_as_float(u & 0xffff0000u); }
; __device__ __forceinline__ u32x4 pack8(f32x4 a, f32x4 b) { u32x4 w; w.x = cvt_pk_bf16(a[0], a[1]); w.y = cvt_pk_bf16(a[2], a[3]); w.z = cvt_pk_bf16(b[0], b[1]); w.w = cvt_pk_bf16(b[2], b[3]); return w; }
;     __device__ __forceinline__ void operator()(AccRef acc, const Unit& u, int wr, int wc, int fr, int fq) const {
;     ...
;             for (int m = 0; m < 4; ++m) {
;                 const size_t off = (size_t)(row0 + ai * HALF + m * 16) * 2048 + col0;
; #pragma unroll
;                 for (int bj = 0; bj < 2; ++bj) {
;                     const u32x4 gv = *(const u32x4*)(G + off + bj * HALF);
;                     f32x4 v0 = acc[ai][bj][m][0], v1 = acc[ai][bj][m][1];
;                     v0[0] *= bf_lo(gv.x); v0[1] *= bf_hi(gv.x); v0[2] *= bf_lo(gv.y); v0[3] *= bf_hi(gv.y);
;                     v1[0] *= bf_lo(gv.z); v1[1] *= bf_hi(gv.z); v1[2] *= bf_lo(gv.w); v1[3] *= bf_hi(gv.w);
;                     if (ADD) {
;                         const u32x4 tv = *(const u32x4*)(T + off + bj * HALF);
;                         v0[0] += bf_lo(tv.x); v0[1] += bf_hi(tv.x); v0[2] += bf_lo(tv.y); v0[3] += bf_hi(tv.y);
;                         v1[0] += bf_lo(tv.z); v1[1] += bf_hi(tv.z); v1[2] += bf_lo(tv.w); v1[3] += bf_hi(tv.w);
;                     }
;                     *(u32x4*)(T + off + bj * HALF) = pack8(v0, v1);
;                 }
	v_lshlrev_b32_e32 v152, 16, v168
	v_and_b32_e32 v168, 0xffff0000, v168
	v_lshlrev_b32_e32 v156, 16, v172
	v_and_b32_e32 v172, 0xffff0000, v172
	v_lshlrev_b32_e32 v153, 16, v169
	v_and_b32_e32 v169, 0xffff0000, v169
	v_lshlrev_b32_e32 v157, 16, v173
	v_and_b32_e32 v173, 0xffff0000, v173
	v_lshlrev_b32_e32 v154, 16, v170
	v_and_b32_e32 v170, 0xffff0000, v170
	v_lshlrev_b32_e32 v158, 16, v174
	v_and_b32_e32 v174, 0xffff0000, v174
	v_lshlrev_b32_e32 v155, 16, v171
	v_and_b32_e32 v171, 0xffff0000, v171
	v_lshlrev_b32_e32 v159, 16, v175
	v_and_b32_e32 v175, 0xffff0000, v175
	v_fmac_f32_e32 v156, v52, v152
	v_fmac_f32_e32 v172, v53, v168
	v_fmac_f32_e32 v157, v54, v153
	v_fmac_f32_e32 v173, v55, v169
	v_fmac_f32_e32 v158, v48, v154
	v_fmac_f32_e32 v174, v49, v170
	v_fmac_f32_e32 v159, v50, v155
	v_fmac_f32_e32 v175, v51, v171
	v_cvt_pk_bf16_f32 v52, v156, v172
	v_cvt_pk_bf16_f32 v53, v157, v173
	v_cvt_pk_bf16_f32 v54, v158, v174
	v_cvt_pk_bf16_f32 v55, v159, v175
	global_store_dwordx4 v227, v[52:55], s[6:7] offset:256
	s_waitcnt vmcnt(16)
	v_lshlrev_b32_e32 v152, 16, v176
	v_and_b32_e32 v176, 0xffff0000, v176
	v_lshlrev_b32_e32 v156, 16, v180
	v_and_b32_e32 v180, 0xffff0000, v180
	v_lshlrev_b32_e32 v153, 16, v177
	v_and_b32_e32 v177, 0xffff0000, v177
	v_lshlrev_b32_e32 v157, 16, v181
	v_and_b32_e32 v181, 0xffff0000, v181
	v_lshlrev_b32_e32 v154, 16, v178
	v_and_b32_e32 v178, 0xffff0000, v178
	v_lshlrev_b32_e32 v158, 16, v182
	v_and_b32_e32 v182, 0xffff0000, v182
	v_lshlrev_b32_e32 v155, 16, v179
	v_and_b32_e32 v179, 0xffff0000, v179
	v_lshlrev_b32_e32 v159, 16, v183
	v_and_b32_e32 v183, 0xffff0000, v183
	v_fmac_f32_e32 v156, v44, v152
	v_fmac_f32_e32 v180, v45, v176
	v_fmac_f32_e32 v157, v46, v153
	v_fmac_f32_e32 v181, v47, v177
	v_fmac_f32_e32 v158, v40, v154
	v_fmac_f32_e32 v182, v41, v178
	v_fmac_f32_e32 v159, v42, v155
	v_fmac_f32_e32 v183, v43, v179
	v_cvt_pk_bf16_f32 v44, v156, v180
	v_cvt_pk_bf16_f32 v45, v157, v181
	v_cvt_pk_bf16_f32 v46, v158, v182
	v_cvt_pk_bf16_f32 v47, v159, v183
	global_store_dwordx4 v228, v[44:47], s[6:7]
	s_waitcnt vmcnt(15)
	v_lshlrev_b32_e32 v152, 16, v184
	v_and_b32_e32 v184, 0xffff0000, v184
	v_lshlrev_b32_e32 v156, 16, v188
	v_and_b32_e32 v188, 0xffff0000, v188
	v_lshlrev_b32_e32 v153, 16, v185
	v_and_b32_e32 v185, 0xffff0000, v185
	v_lshlrev_b32_e32 v157, 16, v189
	v_and_b32_e32 v189, 0xffff0000, v189
	v_lshlrev_b32_e32 v154, 16, v186
	v_and_b32_e32 v186, 0xffff0000, v186
	v_lshlrev_b32_e32 v158, 16, v190
	v_and_b32_e32 v190, 0xffff0000, v190
	v_lshlrev_b32_e32 v155, 16, v187
	v_and_b32_e32 v187, 0xffff0000, v187
	v_lshlrev_b32_e32 v159, 16, v191
	v_and_b32_e32 v191, 0xffff0000, v191
	v_fmac_f32_e32 v156, v36, v152
	v_fmac_f32_e32 v188, v37, v184
	v_fmac_f32_e32 v157, v38, v153
	v_fmac_f32_e32 v189, v39, v185
	v_fmac_f32_e32 v158, v32, v154
	v_fmac_f32_e32 v190, v33, v186
	v_fmac_f32_e32 v159, v34, v155
	v_fmac_f32_e32 v191, v35, v187
	v_cvt_pk_bf16_f32 v36, v156, v188
	v_cvt_pk_bf16_f32 v37, v157, v189
	v_cvt_pk_bf16_f32 v38, v158, v190
	v_cvt_pk_bf16_f32 v39, v159, v191
	global_store_dwordx4 v228, v[36:39], s[6:7] offset:256
	s_waitcnt vmcnt(12)
	v_lshlrev_b32_e32 v152, 16, v192
	v_and_b32_e32 v192, 0xffff0000, v192
	v_lshlrev_b32_e32 v156, 16, v196
	v_and_b32_e32 v196, 0xffff0000, v196
	v_lshlrev_b32_e32 v153, 16, v193
	v_and_b32_e32 v193, 0xffff0000, v193
	v_lshlrev_b32_e32 v157, 16, v197
	v_and_b32_e32 v197, 0xffff0000, v197
	v_lshlrev_b32_e32 v154, 16, v194
	v_and_b32_e32 v194, 0xffff0000, v194
	v_lshlrev_b32_e32 v158, 16, v198
	v_and_b32_e32 v198, 0xffff0000, v198
	v_lshlrev_b32_e32 v155, 16, v195
	v_and_b32_e32 v195, 0xffff0000, v195
	v_lshlrev_b32_e32 v159, 16, v199
	v_and_b32_e32 v199, 0xffff0000, v199
	v_fmac_f32_e32 v156, v28, v152
	v_fmac_f32_e32 v196, v29, v192
	v_fmac_f32_e32 v157, v30, v153
	v_fmac_f32_e32 v197, v31, v193
	v_fmac_f32_e32 v158, v24, v154
	v_fmac_f32_e32 v198, v25, v194
	v_fmac_f32_e32 v159, v26, v155
	v_fmac_f32_e32 v199, v27, v195
	v_cvt_pk_bf16_f32 v28, v156, v196
	v_cvt_pk_bf16_f32 v29, v157, v197
	v_cvt_pk_bf16_f32 v30, v158, v198
	v_cvt_pk_bf16_f32 v31, v159, v199
	global_store_dwordx4 v229, v[28:31], s[6:7]
	s_waitcnt vmcnt(11)
; __device__ __forceinline__ float bf_lo(unsigned u) { return __uint_as_float(u << 16); }
; __device__ __forceinline__ float bf_hi(unsigned u) { return __uint_as_float(u & 0xffff0000u); }
; __device__ __forceinline__ u32x4 pack8(f32x4 a, f32x4 b) { u32x4 w; w.x = cvt_pk_bf16(a[0], a[1]); w.y = cvt_pk_bf16(a[2], a[3]); w.z = cvt_pk_bf16(b[0], b[1]); w.w = cvt_pk_bf16(b[2], b[3]); return w; }
; #define PG8_BAR __builtin_amdgcn_s_barrier()
; template <class Epi>
; __device__ __forceinline__ void gemm_phase(ldsp lds, const Gemm g, const StaticOrder& S, const Epi& E, int wave0) {
;     ...
;         if (!has_next) break;
; #pragma unroll
;         for (int a = 0; a < 2; ++a)
; #pragma unroll
;             for (int b = 0; b < 2; ++b)
; #pragma unroll
;                 for (int m = 0; m < 4; ++m)
; #pragma unroll
;                     for (int n = 0; n < 2; ++n) acc[a][b][m][n] = (f32x4){0.f, 0.f, 0.f, 0.f};
;         cur = nxt; cA = nA; cB = nB; ++ui;
;         if (wr == 1) PG8_BAR;
;     __device__ __forceinline__ void operator()(AccRef acc, const Unit& u, int wr, int wc, int fr, int fq) const {
;     ...
;                 for (int bj = 0; bj < 2; ++bj) {
;                     const u32x4 gv = *(const u32x4*)(G + off + bj * HALF);
;                     f32x4 v0 = acc[ai][bj][m][0], v1 = acc[ai][bj][m][1];
;                     v0[0] *= bf_lo(gv.x); v0[1] *= bf_hi(gv.x); v0[2] *= bf_lo(gv.y); v0[3] *= bf_hi(gv.y);
;                     v1[0] *= bf_lo(gv.z); v1[1] *= bf_hi(gv.z); v1[2] *= bf_lo(gv.w); v1[3] *= bf_hi(gv.w);
;                     if (ADD) {
;                         const u32x4 tv = *(const u32x4*)(T + off + bj * HALF);
;                         v0[0] += bf_lo(tv.x); v0[1] += bf_hi(tv.x); v0[2] += bf_lo(tv.y); v0[3] += bf_hi(tv.y);
;                         v1[0] += bf_lo(tv.z); v1[1] += bf_hi(tv.z); v1[2] += bf_lo(tv.w); v1[3] += bf_hi(tv.w);
;                     }
;                     *(u32x4*)(T + off + bj * HALF) = pack8(v0, v1);
;                 }
	v_lshlrev_b32_e32 v152, 16, v200
	v_and_b32_e32 v200, 0xffff0000, v200
	v_lshlrev_b32_e32 v156, 16, v204
	v_and_b32_e32 v204, 0xffff0000, v204
	v_lshlrev_b32_e32 v153, 16, v201
	v_and_b32_e32 v201, 0xffff0000, v201
	v_lshlrev_b32_e32 v157, 16, v205
	v_and_b32_e32 v205, 0xffff0000, v205
	v_lshlrev_b32_e32 v154, 16, v202
	v_and_b32_e32 v202, 0xffff0000, v202
	v_lshlrev_b32_e32 v158, 16, v206
	v_and_b32_e32 v206, 0xffff0000, v206
	v_lshlrev_b32_e32 v155, 16, v203
	v_and_b32_e32 v203, 0xffff0000, v203
	v_lshlrev_b32_e32 v159, 16, v207
	v_and_b32_e32 v207, 0xffff0000, v207
	v_fmac_f32_e32 v156, v20, v152
	v_fmac_f32_e32 v204, v21, v200
	v_fmac_f32_e32 v157, v22, v153
	v_fmac_f32_e32 v205, v23, v201
	v_fmac_f32_e32 v158, v16, v154
	v_fmac_f32_e32 v206, v17, v202
	v_fmac_f32_e32 v159, v18, v155
	v_fmac_f32_e32 v207, v19, v203
	v_cvt_pk_bf16_f32 v20, v156, v204
	v_cvt_pk_bf16_f32 v21, v157, v205
	v_cvt_pk_bf16_f32 v22, v158, v206
	v_cvt_pk_bf16_f32 v23, v159, v207
	global_store_dwordx4 v229, v[20:23], s[6:7] offset:256
	s_waitcnt vmcnt(8)
	v_lshlrev_b32_e32 v152, 16, v208
	v_and_b32_e32 v208, 0xffff0000, v208
	v_lshlrev_b32_e32 v156, 16, v212
	v_and_b32_e32 v212, 0xffff0000, v212
	v_lshlrev_b32_e32 v153, 16, v209
	v_and_b32_e32 v209, 0xffff0000, v209
	v_lshlrev_b32_e32 v157, 16, v213
	v_and_b32_e32 v213, 0xffff0000, v213
	v_lshlrev_b32_e32 v154, 16, v210
	v_and_b32_e32 v210, 0xffff0000, v210
	v_lshlrev_b32_e32 v158, 16, v214
	v_and_b32_e32 v214, 0xffff0000, v214
	v_lshlrev_b32_e32 v155, 16, v211
	v_and_b32_e32 v211, 0xffff0000, v211
	v_lshlrev_b32_e32 v159, 16, v215
	v_and_b32_e32 v215, 0xffff0000, v215
	v_fmac_f32_e32 v156, v12, v152
	v_fmac_f32_e32 v212, v13, v208
	v_fmac_f32_e32 v157, v14, v153
	v_fmac_f32_e32 v213, v15, v209
	v_fmac_f32_e32 v158, v8, v154
	v_fmac_f32_e32 v214, v9, v210
	v_fmac_f32_e32 v159, v10, v155
	v_fmac_f32_e32 v215, v11, v211
	v_cvt_pk_bf16_f32 v12, v156, v212
	v_cvt_pk_bf16_f32 v13, v157, v213
	v_cvt_pk_bf16_f32 v14, v158, v214
	v_cvt_pk_bf16_f32 v15, v159, v215
	global_store_dwordx4 v230, v[12:15], s[6:7]
	s_waitcnt vmcnt(7)
	v_lshlrev_b32_e32 v152, 16, v216
	v_and_b32_e32 v216, 0xffff0000, v216
	v_lshlrev_b32_e32 v156, 16, v220
	v_and_b32_e32 v220, 0xffff0000, v220
	v_lshlrev_b32_e32 v153, 16, v217
	v_and_b32_e32 v217, 0xffff0000, v217
	v_lshlrev_b32_e32 v157, 16, v221
	v_and_b32_e32 v221, 0xffff0000, v221
	v_lshlrev_b32_e32 v154, 16, v218
	v_and_b32_e32 v218, 0xffff0000, v218
	v_lshlrev_b32_e32 v158, 16, v222
	v_and_b32_e32 v222, 0xffff0000, v222
	v_lshlrev_b32_e32 v155, 16, v219
	v_and_b32_e32 v219, 0xffff0000, v219
	v_lshlrev_b32_e32 v159, 16, v223
	v_and_b32_e32 v223, 0xffff0000, v223
	v_fmac_f32_e32 v156, v4, v152
	v_fmac_f32_e32 v220, v5, v216
	v_fmac_f32_e32 v157, v6, v153
	v_fmac_f32_e32 v221, v7, v217
	v_fmac_f32_e32 v158, v0, v154
	v_fmac_f32_e32 v222, v1, v218
	v_fmac_f32_e32 v159, v2, v155
	v_fmac_f32_e32 v223, v3, v219
	v_cvt_pk_bf16_f32 v4, v156, v220
	v_cvt_pk_bf16_f32 v5, v157, v221
	v_cvt_pk_bf16_f32 v6, v158, v222
	v_cvt_pk_bf16_f32 v7, v159, v223
	global_store_dwordx4 v230, v[4:7], s[6:7] offset:256
	s_cbranch_vccnz .LBB0_705
	s_andn2_b64 vcc, exec, s[2:3]
	s_cbranch_vccnz .LBB0_704
	s_barrier
	s_branch .LBB0_704
